# v19 with the MLA loop-control scalar ops and exit test rotated ahead of the per-tile barrier (back-edge rotation)
# speedup vs baseline: 1.0038x; 1.0038x over previous
.LBB0_461:
	s_add_i32 s14, s14, 64
	s_addk_i32 s71, 0x2000
	s_addk_i32 s72, 0x4000
	s_cmp_lg_u32 s70, s74
	s_waitcnt lgkmcnt(0)
	s_barrier
	s_cbranch_scc0 .LBB0_470
	s_mov_b32 s73, s74
	s_branch .Lmo_437
